# v8: GEMM mode0/1 epilogue rewritten: ssq partials via LDS-DMA once per phase, scalar-base stores, no canonicalize
# baseline (speedup 1.0000x reference)
_Z8mega_fwd4Args:
	s_add_u32 s4, s0, 0xa0
	v_writelane_b32 v247, s2, 0
	s_load_dwordx8 s[16:23], s[0:1], 0x80
	s_load_dwordx2 s[2:3], s[0:1], 0xa0
	v_and_b32_e32 v195, 0x3ff, v0
	s_addc_u32 s5, s1, 0
	v_cmp_gt_u32_e32 vcc, 2, v195
	s_waitcnt lgkmcnt(0)
	v_writelane_b32 v247, s2, 1
	s_nop 1
	v_writelane_b32 v247, s3, 2
	s_and_saveexec_b64 s[2:3], vcc
	v_writelane_b32 v248, 0, 2
	v_writelane_b32 v248, 0, 3
	s_or_b64 exec, exec, s[2:3]
	s_cmp_gt_i32 s22, -1
	s_waitcnt lgkmcnt(0)
	s_barrier
	s_cbranch_scc1 .LBB0_14
	v_lshrrev_b32_e32 v1, 20, v0
	v_lshrrev_b32_e32 v0, 10, v0
	v_or_b32_e32 v0, v0, v1
	s_movk_i32 s2, 0x3ff
	v_and_or_b32 v0, v0, s2, v195
	v_cmp_eq_u32_e32 vcc, 0, v0
	s_barrier
	s_and_saveexec_b64 s[2:3], vcc
	s_cbranch_execz .LBB0_13
	buffer_wbl2 sc1
	s_load_dwordx2 s[4:5], s[4:5], 0x58
	s_mov_b64 s[6:7], exec
	v_mbcnt_lo_u32_b32 v0, s6, 0
	v_mbcnt_hi_u32_b32 v0, s7, v0
	v_cmp_eq_u32_e32 vcc, 0, v0
	s_waitcnt lgkmcnt(0)
	s_load_dword s10, s[4:5], 0x28
	s_and_saveexec_b64 s[8:9], vcc
	s_cbranch_execz .LBB0_6
	s_bcnt1_i32_b64 s6, s[6:7]
	v_mov_b32_e32 v1, 0
	v_mov_b32_e32 v2, s6
	global_atomic_add v1, v1, v2, s[4:5] offset:32 sc0

.LBB0_51:
	s_andn2_b64 vcc, exec, s[30:31]
	s_cbranch_vccnz .LBB0_123
	s_cmp_eq_u64 s[14:15], 0
	s_cbranch_scc1 .Lmy_ssq_skip
	v_and_b32_e32 v128, 63, v13
	v_lshlrev_b32_e32 v128, 4, v128
	s_lshl_b32 s33, s2, 5
	s_lshl_b32 s46, s68, 14
	s_add_u32 s46, s14, s46
	s_addc_u32 s47, s15, 0
	s_add_u32 s46, s46, s33
	s_addc_u32 s47, s47, 0
	s_lshl_b32 m0, s68, 11
	s_and_b32 m0, m0, 0x4000
	s_add_i32 m0, m0, s33
	s_add_i32 m0, m0, 0x20000
	s_nop 0
	global_load_lds_dwordx4 v128, s[46:47]
	global_load_lds_dwordx4 v128, s[46:47] offset:1024
	s_cmp_lt_u32 s68, 120
	s_cbranch_scc0 .Lmy_ssq_skip
	s_add_u32 s46, s46, 0x20000
	s_addc_u32 s47, s47, 0
	s_xor_b32 m0, m0, 0x4000
	s_nop 0
	global_load_lds_dwordx4 v128, s[46:47]
	global_load_lds_dwordx4 v128, s[46:47] offset:1024
.Lmy_ssq_skip:
	v_bfe_i32 v2, v13, 27, 1
	v_lshlrev_b32_e32 v0, 4, v13
	v_lshrrev_b32_e32 v2, 22, v2
	v_add_u32_e32 v2, v0, v2
	v_and_b32_e32 v2, 0xfffffc00, v2
	v_sub_u32_e32 v2, v0, v2
	s_waitcnt lgkmcnt(0)
	v_ashrrev_i32_e32 v1, 31, v13
	v_lshrrev_b32_e32 v3, 4, v2
	v_lshrrev_b32_e32 v1, 26, v1
	v_bitop3_b32 v2, v3, v2, 32 bitop3:0x6c
	v_add_u32_e32 v1, v13, v1
	v_ashrrev_i32_e32 v4, 31, v2
	v_ashrrev_i32_e32 v1, 6, v1
	v_lshrrev_b32_e32 v4, 26, v4
	v_lshlrev_b32_e32 v3, 3, v1
	v_add_u32_e32 v4, v2, v4
	v_and_b32_e32 v3, -16, v3
	v_ashrrev_i32_e32 v5, 6, v4
	v_lshlrev_b32_e32 v1, 5, v1
	v_add_u32_e32 v3, v5, v3
	v_and_b32_e32 v14, 32, v1
	v_and_b32_e32 v1, 0xc0, v4
	v_sub_u32_e32 v1, v2, v1
	v_lshlrev_b32_e32 v2, 1, v3
	v_lshrrev_b32_e32 v4, 2, v3
	v_and_b32_e32 v5, 3, v5
	s_mov_b32 s19, 0x7fffffe0
	v_ashrrev_i16_sdwa v1, v203, sext(v1) dst_sel:DWORD dst_unused:UNUSED_PAD src0_sel:DWORD src1_sel:BYTE_0
	v_and_b32_e32 v2, 24, v2
	v_and_b32_e32 v4, 4, v4
	v_and_or_b32 v5, v3, s19, v5
	v_bfe_i32 v15, v1, 0, 16
	v_or3_b32 v2, v5, v4, v2
	v_add_u32_e32 v1, v14, v15
	v_mul_lo_u32 v16, v3, s3
	v_mul_lo_u32 v2, v2, s3
	v_add_u32_e32 v0, 0x2000, v0
	v_add_lshl_u32 v156, v1, v16, 1
	v_add_lshl_u32 v192, v2, v1, 1
	v_ashrrev_i32_e32 v1, 31, v0
	v_lshrrev_b32_e32 v1, 22, v1
	v_add_u32_e32 v1, v0, v1
	v_ashrrev_i32_e32 v1, 10, v1
	v_mul_i32_i24_e32 v2, 0x400, v1
	v_sub_u32_e32 v0, v0, v2
	s_lshl_b32 s30, s3, 8
	s_mov_b32 s31, s4
	v_lshrrev_b32_e32 v2, 4, v0
	s_lshl_b64 s[44:45], s[30:31], 1
	s_ashr_i32 s28, s68, 31
	v_bitop3_b32 v0, v2, v0, 32 bitop3:0x6c
	s_mul_i32 s28, s44, s28
	s_mul_hi_u32 s33, s44, s68
	v_writelane_b32 v245, s36, 31
	v_ashrrev_i32_e32 v3, 31, v0
	s_add_i32 s28, s33, s28
	s_bfe_u32 s33, s3, 0x10017
	v_writelane_b32 v245, s37, 32
	v_lshrrev_b32_e32 v3, 26, v3
	s_mul_i32 s36, s33, s68
	v_lshlrev_b32_e32 v2, 3, v1
	v_add_u32_e32 v3, v0, v3
	s_add_i32 s38, s28, s36
	s_ashr_i32 s28, s26, 31
	v_and_b32_e32 v2, -16, v2
	v_ashrrev_i32_e32 v4, 6, v3
	s_mul_i32 s28, s44, s28
	s_mul_hi_u32 s36, s44, s26
	s_ashr_i32 s5, s2, 6
	v_add_u32_e32 v2, v4, v2
	v_lshlrev_b32_e32 v1, 5, v1
	v_and_b32_e32 v4, 3, v4
	s_add_i32 s28, s36, s28
	s_mul_i32 s33, s33, s26
	v_and_b32_e32 v17, 32, v1
	v_and_b32_e32 v1, 0xc0, v3
	v_and_or_b32 v4, v2, s19, v4
	s_ashr_i32 s19, s2, 8
	s_lshl_b32 s27, s5, 10
	s_add_i32 s28, s28, s33
	s_mul_i32 s33, s44, s26
	v_sub_u32_e32 v0, v0, v1
	v_lshlrev_b32_e32 v1, 1, v2
	v_lshrrev_b32_e32 v3, 2, v2
	s_add_u32 s42, s6, s33
	v_ashrrev_i16_sdwa v0, v203, sext(v0) dst_sel:DWORD dst_unused:UNUSED_PAD src0_sel:DWORD src1_sel:BYTE_0
	v_and_b32_e32 v1, 24, v1
	v_and_b32_e32 v3, 4, v3
	s_addc_u32 s43, s7, s28
	s_add_i32 s28, s27, 0
	v_bfe_i32 v18, v0, 0, 16
	v_or3_b32 v1, v4, v3, v1
	s_add_i32 m0, s28, 0x10000
	v_add_u32_e32 v0, v17, v18
	v_mul_lo_u32 v1, v1, s3
	global_load_lds_dwordx4 v192, s[42:43]
	s_add_i32 m0, s28, 0x12000
	v_add_lshl_u32 v160, v1, v0, 1
	s_add_u32 s36, s42, s30
	global_load_lds_dwordx4 v160, s[42:43]
	s_addc_u32 s37, s43, 0
	s_add_i32 m0, s28, 0x14000
	s_mul_i32 s39, s44, s68
	global_load_lds_dwordx4 v192, s[36:37]
	s_add_i32 m0, s28, 0x16000
	s_add_u32 s40, s12, s39
	v_mov_b32_e32 v161, v193
	s_addc_u32 s41, s13, s38
	s_add_i32 s69, s28, 0x2000
	v_mul_lo_u32 v19, v2, s3
	v_lshl_add_u64 v[4:5], s[36:37], 0, v[192:193]
	v_lshl_add_u64 v[6:7], s[36:37], 0, v[160:161]
	global_load_lds_dwordx4 v160, s[36:37]
	s_mov_b32 m0, s28
	s_add_u32 s36, s40, s30
	v_add_lshl_u32 v158, v0, v19, 1
	global_load_lds_dwordx4 v156, s[40:41]
	s_mov_b32 m0, s69
	s_addc_u32 s37, s41, 0
	s_add_i32 s72, s28, 0x4000
	global_load_lds_dwordx4 v158, s[40:41]
	s_mov_b32 m0, s72
	s_add_i32 s76, s28, 0x6000
	global_load_lds_dwordx4 v156, s[36:37]
	s_mov_b32 m0, s76
	s_cmp_eq_u32 s19, 1
	global_load_lds_dwordx4 v158, s[36:37]
	v_writelane_b32 v245, s65, 33
	v_mov_b32_e32 v157, v193
	v_mov_b32_e32 v159, v193
	s_cselect_b64 s[36:37], -1, 0
	v_lshl_add_u64 v[0:1], s[42:43], 0, v[192:193]
	v_lshl_add_u64 v[2:3], s[42:43], 0, v[160:161]
	v_lshl_add_u64 v[8:9], s[40:41], 0, v[156:157]
	v_lshl_add_u64 v[10:11], s[40:41], 0, v[158:159]
	v_writelane_b32 v245, s36, 34
	s_cmp_lg_u32 s19, 1
	s_nop 0
	v_writelane_b32 v245, s37, 35
	s_cbranch_scc1 .LBB0_54
	s_barrier

.LBB0_67:
	s_lshl_b32 s33, s68, 8
	s_add_i32 s33, s33, s79
	v_or_b32_e32 v168, s33, v184
	v_lshl_or_b32 v166, s26, 8, v186
	s_mov_b64 s[40:41], -1
	s_and_b64 vcc, exec, s[64:65]
	s_cbranch_vccz .LBB0_101
	s_lshl_b32 s42, s68, 11
	s_and_b32 s42, s42, 0x4000
	s_lshl_b32 s43, s79, 6
	s_add_i32 s42, s42, s43
	s_add_i32 s42, s42, 0x20000
	v_lshl_add_u32 v128, v187, 6, s42
	ds_read_b128 v[132:135], v128 offset:0
	ds_read_b128 v[136:139], v128 offset:16
	ds_read_b128 v[140:143], v128 offset:32
	ds_read_b128 v[144:147], v128 offset:48
	ds_read_b128 v[148:151], v128 offset:8192
	ds_read_b128 v[152:155], v128 offset:8208
	ds_read_b128 v[170:173], v128 offset:8224
	ds_read_b128 v[174:177], v128 offset:8240
	v_mul_u32_u24_e32 v129, s24, v184
	v_and_b32_e32 v130, 24, v186
	v_add_lshl_u32 v129, v129, v130, 1
	s_mul_i32 s42, s33, s24
	s_lshl_b32 s43, s26, 8
	s_add_i32 s42, s42, s43
	s_lshl_b32 s43, s77, 5
	s_add_i32 s42, s42, s43
	s_lshl_b32 s42, s42, 1
	s_add_u32 s42, s16, s42
	s_addc_u32 s43, s17, 0
	s_lshl_b32 s46, s24, 5
	s_lshl_b32 s47, s24, 7
	v_lshlrev_b32_e32 v131, 2, v184
	s_waitcnt lgkmcnt(4)
	v_add_f32_e32 v132, v132, v133
	v_add_f32_e32 v134, v134, v135
	v_add_f32_e32 v132, v132, v134
	v_add_f32_e32 v136, v136, v137
	v_add_f32_e32 v138, v138, v139
	v_add_f32_e32 v136, v136, v138
	v_add_f32_e32 v140, v140, v141
	v_add_f32_e32 v142, v142, v143
	v_add_f32_e32 v140, v140, v142
	v_add_f32_e32 v144, v144, v145
	v_add_f32_e32 v146, v146, v147
	v_add_f32_e32 v144, v144, v146
	v_add_f32_e32 v132, v132, v136
	v_add_f32_e32 v140, v140, v144
	v_add_f32_e32 v132, v132, v140
	v_fmamk_f32 v132, v132, 0x3a800000, v194
	v_rsq_f32_e32 v178, v132
	s_waitcnt lgkmcnt(0)
	v_add_f32_e32 v148, v148, v149
	v_add_f32_e32 v150, v150, v151
	v_add_f32_e32 v148, v148, v150
	v_add_f32_e32 v152, v152, v153
	v_add_f32_e32 v154, v154, v155
	v_add_f32_e32 v152, v152, v154
	v_add_f32_e32 v170, v170, v171
	v_add_f32_e32 v172, v172, v173
	v_add_f32_e32 v170, v170, v172
	v_add_f32_e32 v174, v174, v175
	v_add_f32_e32 v176, v176, v177
	v_add_f32_e32 v174, v174, v176
	v_add_f32_e32 v148, v148, v152
	v_add_f32_e32 v170, v170, v174
	v_add_f32_e32 v148, v148, v170
	v_fmamk_f32 v148, v148, 0x3a800000, v194
	v_rsq_f32_e32 v180, v148
	s_nop 1
	ds_bpermute_b32 v214, v131, v178
	ds_bpermute_b32 v216, v131, v178 offset:64
	ds_bpermute_b32 v218, v131, v178 offset:128
	ds_bpermute_b32 v220, v131, v178 offset:192
	ds_bpermute_b32 v222, v131, v180
	ds_bpermute_b32 v224, v131, v180 offset:64
	ds_bpermute_b32 v226, v131, v180 offset:128
	ds_bpermute_b32 v228, v131, v180 offset:192
	s_and_b64 vcc, exec, s[8:9]
	s_cbranch_vccnz .Lmy_epi_m1
	s_waitcnt lgkmcnt(7)
	v_pk_mul_f32 v[132:133], v[124:125], v[214:215] op_sel_hi:[1,0]
	v_pk_mul_f32 v[134:135], v[126:127], v[214:215] op_sel_hi:[1,0]
	v_pk_mul_f32 v[136:137], v[120:121], v[214:215] op_sel_hi:[1,0]
	v_pk_mul_f32 v[138:139], v[122:123], v[214:215] op_sel_hi:[1,0]
	v_cvt_pk_bf16_f32 v140, v132, v133
	v_cvt_pk_bf16_f32 v141, v134, v135
	v_cvt_pk_bf16_f32 v142, v136, v137
	v_cvt_pk_bf16_f32 v143, v138, v139
	global_store_dwordx4 v129, v[140:143], s[42:43]
	v_pk_mul_f32 v[144:145], v[116:117], v[214:215] op_sel_hi:[1,0]
	v_pk_mul_f32 v[146:147], v[118:119], v[214:215] op_sel_hi:[1,0]
	v_pk_mul_f32 v[148:149], v[112:113], v[214:215] op_sel_hi:[1,0]
	v_pk_mul_f32 v[150:151], v[114:115], v[214:215] op_sel_hi:[1,0]
	v_cvt_pk_bf16_f32 v152, v144, v145
	v_cvt_pk_bf16_f32 v153, v146, v147
	v_cvt_pk_bf16_f32 v154, v148, v149
	v_cvt_pk_bf16_f32 v155, v150, v151
	global_store_dwordx4 v129, v[152:155], s[42:43] offset:256
	s_add_u32 s42, s42, s46
	s_addc_u32 s43, s43, 0
	s_waitcnt lgkmcnt(6)
	v_pk_mul_f32 v[132:133], v[108:109], v[216:217] op_sel_hi:[1,0]
	v_pk_mul_f32 v[134:135], v[110:111], v[216:217] op_sel_hi:[1,0]
	v_pk_mul_f32 v[136:137], v[104:105], v[216:217] op_sel_hi:[1,0]
	v_pk_mul_f32 v[138:139], v[106:107], v[216:217] op_sel_hi:[1,0]
	v_cvt_pk_bf16_f32 v140, v132, v133
	v_cvt_pk_bf16_f32 v141, v134, v135
	v_cvt_pk_bf16_f32 v142, v136, v137
	v_cvt_pk_bf16_f32 v143, v138, v139
	global_store_dwordx4 v129, v[140:143], s[42:43]
	v_pk_mul_f32 v[144:145], v[100:101], v[216:217] op_sel_hi:[1,0]
	v_pk_mul_f32 v[146:147], v[102:103], v[216:217] op_sel_hi:[1,0]
	v_pk_mul_f32 v[148:149], v[96:97], v[216:217] op_sel_hi:[1,0]
	v_pk_mul_f32 v[150:151], v[98:99], v[216:217] op_sel_hi:[1,0]
	v_cvt_pk_bf16_f32 v152, v144, v145
	v_cvt_pk_bf16_f32 v153, v146, v147
	v_cvt_pk_bf16_f32 v154, v148, v149
	v_cvt_pk_bf16_f32 v155, v150, v151
	global_store_dwordx4 v129, v[152:155], s[42:43] offset:256
	s_add_u32 s42, s42, s46
	s_addc_u32 s43, s43, 0
	s_waitcnt lgkmcnt(5)
	v_pk_mul_f32 v[132:133], v[92:93], v[218:219] op_sel_hi:[1,0]
	v_pk_mul_f32 v[134:135], v[94:95], v[218:219] op_sel_hi:[1,0]
	v_pk_mul_f32 v[136:137], v[88:89], v[218:219] op_sel_hi:[1,0]
	v_pk_mul_f32 v[138:139], v[90:91], v[218:219] op_sel_hi:[1,0]
	v_cvt_pk_bf16_f32 v140, v132, v133
	v_cvt_pk_bf16_f32 v141, v134, v135
	v_cvt_pk_bf16_f32 v142, v136, v137
	v_cvt_pk_bf16_f32 v143, v138, v139
	global_store_dwordx4 v129, v[140:143], s[42:43]
	v_pk_mul_f32 v[144:145], v[84:85], v[218:219] op_sel_hi:[1,0]
	v_pk_mul_f32 v[146:147], v[86:87], v[218:219] op_sel_hi:[1,0]
	v_pk_mul_f32 v[148:149], v[80:81], v[218:219] op_sel_hi:[1,0]
	v_pk_mul_f32 v[150:151], v[82:83], v[218:219] op_sel_hi:[1,0]
	v_cvt_pk_bf16_f32 v152, v144, v145
	v_cvt_pk_bf16_f32 v153, v146, v147
	v_cvt_pk_bf16_f32 v154, v148, v149
	v_cvt_pk_bf16_f32 v155, v150, v151
	global_store_dwordx4 v129, v[152:155], s[42:43] offset:256
	s_add_u32 s42, s42, s46
	s_addc_u32 s43, s43, 0
	s_waitcnt lgkmcnt(4)
	v_pk_mul_f32 v[132:133], v[76:77], v[220:221] op_sel_hi:[1,0]
	v_pk_mul_f32 v[134:135], v[78:79], v[220:221] op_sel_hi:[1,0]
	v_pk_mul_f32 v[136:137], v[72:73], v[220:221] op_sel_hi:[1,0]
	v_pk_mul_f32 v[138:139], v[74:75], v[220:221] op_sel_hi:[1,0]
	v_cvt_pk_bf16_f32 v140, v132, v133
	v_cvt_pk_bf16_f32 v141, v134, v135
	v_cvt_pk_bf16_f32 v142, v136, v137
	v_cvt_pk_bf16_f32 v143, v138, v139
	global_store_dwordx4 v129, v[140:143], s[42:43]
	v_pk_mul_f32 v[144:145], v[68:69], v[220:221] op_sel_hi:[1,0]
	v_pk_mul_f32 v[146:147], v[70:71], v[220:221] op_sel_hi:[1,0]
	v_pk_mul_f32 v[148:149], v[64:65], v[220:221] op_sel_hi:[1,0]
	v_pk_mul_f32 v[150:151], v[66:67], v[220:221] op_sel_hi:[1,0]
	v_cvt_pk_bf16_f32 v152, v144, v145
	v_cvt_pk_bf16_f32 v153, v146, v147
	v_cvt_pk_bf16_f32 v154, v148, v149
	v_cvt_pk_bf16_f32 v155, v150, v151
	global_store_dwordx4 v129, v[152:155], s[42:43] offset:256
	s_add_u32 s42, s42, s46
	s_addc_u32 s43, s43, 0
	s_add_u32 s42, s42, s47
	s_addc_u32 s43, s43, 0
	s_waitcnt lgkmcnt(3)
	v_pk_mul_f32 v[132:133], v[60:61], v[222:223] op_sel_hi:[1,0]
	v_pk_mul_f32 v[134:135], v[62:63], v[222:223] op_sel_hi:[1,0]
	v_pk_mul_f32 v[136:137], v[56:57], v[222:223] op_sel_hi:[1,0]
	v_pk_mul_f32 v[138:139], v[58:59], v[222:223] op_sel_hi:[1,0]
	v_cvt_pk_bf16_f32 v140, v132, v133
	v_cvt_pk_bf16_f32 v141, v134, v135
	v_cvt_pk_bf16_f32 v142, v136, v137
	v_cvt_pk_bf16_f32 v143, v138, v139
	global_store_dwordx4 v129, v[140:143], s[42:43]
	v_pk_mul_f32 v[144:145], v[52:53], v[222:223] op_sel_hi:[1,0]
	v_pk_mul_f32 v[146:147], v[54:55], v[222:223] op_sel_hi:[1,0]
	v_pk_mul_f32 v[148:149], v[48:49], v[222:223] op_sel_hi:[1,0]
	v_pk_mul_f32 v[150:151], v[50:51], v[222:223] op_sel_hi:[1,0]
	v_cvt_pk_bf16_f32 v152, v144, v145
	v_cvt_pk_bf16_f32 v153, v146, v147
	v_cvt_pk_bf16_f32 v154, v148, v149
	v_cvt_pk_bf16_f32 v155, v150, v151
	global_store_dwordx4 v129, v[152:155], s[42:43] offset:256
	s_add_u32 s42, s42, s46
	s_addc_u32 s43, s43, 0
	s_waitcnt lgkmcnt(2)
	v_pk_mul_f32 v[132:133], v[44:45], v[224:225] op_sel_hi:[1,0]
	v_pk_mul_f32 v[134:135], v[46:47], v[224:225] op_sel_hi:[1,0]
	v_pk_mul_f32 v[136:137], v[40:41], v[224:225] op_sel_hi:[1,0]
	v_pk_mul_f32 v[138:139], v[42:43], v[224:225] op_sel_hi:[1,0]
	v_cvt_pk_bf16_f32 v140, v132, v133
	v_cvt_pk_bf16_f32 v141, v134, v135
	v_cvt_pk_bf16_f32 v142, v136, v137
	v_cvt_pk_bf16_f32 v143, v138, v139
	global_store_dwordx4 v129, v[140:143], s[42:43]
	v_pk_mul_f32 v[144:145], v[36:37], v[224:225] op_sel_hi:[1,0]
	v_pk_mul_f32 v[146:147], v[38:39], v[224:225] op_sel_hi:[1,0]
	v_pk_mul_f32 v[148:149], v[32:33], v[224:225] op_sel_hi:[1,0]
	v_pk_mul_f32 v[150:151], v[34:35], v[224:225] op_sel_hi:[1,0]
	v_cvt_pk_bf16_f32 v152, v144, v145
	v_cvt_pk_bf16_f32 v153, v146, v147
	v_cvt_pk_bf16_f32 v154, v148, v149
	v_cvt_pk_bf16_f32 v155, v150, v151
	global_store_dwordx4 v129, v[152:155], s[42:43] offset:256
	s_add_u32 s42, s42, s46
	s_addc_u32 s43, s43, 0
	s_waitcnt lgkmcnt(1)
	v_pk_mul_f32 v[132:133], v[28:29], v[226:227] op_sel_hi:[1,0]
	v_pk_mul_f32 v[134:135], v[30:31], v[226:227] op_sel_hi:[1,0]
	v_pk_mul_f32 v[136:137], v[24:25], v[226:227] op_sel_hi:[1,0]
	v_pk_mul_f32 v[138:139], v[26:27], v[226:227] op_sel_hi:[1,0]
	v_cvt_pk_bf16_f32 v140, v132, v133
	v_cvt_pk_bf16_f32 v141, v134, v135
	v_cvt_pk_bf16_f32 v142, v136, v137
	v_cvt_pk_bf16_f32 v143, v138, v139
	global_store_dwordx4 v129, v[140:143], s[42:43]
	v_pk_mul_f32 v[144:145], v[20:21], v[226:227] op_sel_hi:[1,0]
	v_pk_mul_f32 v[146:147], v[22:23], v[226:227] op_sel_hi:[1,0]
	v_pk_mul_f32 v[148:149], v[16:17], v[226:227] op_sel_hi:[1,0]
	v_pk_mul_f32 v[150:151], v[18:19], v[226:227] op_sel_hi:[1,0]
	v_cvt_pk_bf16_f32 v152, v144, v145
	v_cvt_pk_bf16_f32 v153, v146, v147
	v_cvt_pk_bf16_f32 v154, v148, v149
	v_cvt_pk_bf16_f32 v155, v150, v151
	global_store_dwordx4 v129, v[152:155], s[42:43] offset:256
	s_add_u32 s42, s42, s46
	s_addc_u32 s43, s43, 0
	s_waitcnt lgkmcnt(0)
	v_pk_mul_f32 v[132:133], v[12:13], v[228:229] op_sel_hi:[1,0]
	v_pk_mul_f32 v[134:135], v[14:15], v[228:229] op_sel_hi:[1,0]
	v_pk_mul_f32 v[136:137], v[8:9], v[228:229] op_sel_hi:[1,0]
	v_pk_mul_f32 v[138:139], v[10:11], v[228:229] op_sel_hi:[1,0]
	v_cvt_pk_bf16_f32 v140, v132, v133
	v_cvt_pk_bf16_f32 v141, v134, v135
	v_cvt_pk_bf16_f32 v142, v136, v137
	v_cvt_pk_bf16_f32 v143, v138, v139
	global_store_dwordx4 v129, v[140:143], s[42:43]
	v_pk_mul_f32 v[144:145], v[4:5], v[228:229] op_sel_hi:[1,0]
	v_pk_mul_f32 v[146:147], v[6:7], v[228:229] op_sel_hi:[1,0]
	v_pk_mul_f32 v[148:149], v[0:1], v[228:229] op_sel_hi:[1,0]
	v_pk_mul_f32 v[150:151], v[2:3], v[228:229] op_sel_hi:[1,0]
	v_cvt_pk_bf16_f32 v152, v144, v145
	v_cvt_pk_bf16_f32 v153, v146, v147
	v_cvt_pk_bf16_f32 v154, v148, v149
	v_cvt_pk_bf16_f32 v155, v150, v151
	global_store_dwordx4 v129, v[152:155], s[42:43] offset:256
	s_mov_b64 s[40:41], 0
	s_branch .LBB0_101
.Lmy_epi_m1:
	s_waitcnt lgkmcnt(7)
	v_pk_mul_f32 v[132:133], v[124:125], v[214:215] op_sel_hi:[1,0]
	v_pk_mul_f32 v[134:135], v[126:127], v[214:215] op_sel_hi:[1,0]
	v_pk_mul_f32 v[136:137], v[120:121], v[214:215] op_sel_hi:[1,0]
	v_pk_mul_f32 v[138:139], v[122:123], v[214:215] op_sel_hi:[1,0]
	v_max_f32_e32 v132, 0, v132
	v_max_f32_e32 v133, 0, v133
	v_max_f32_e32 v134, 0, v134
	v_max_f32_e32 v135, 0, v135
	v_max_f32_e32 v136, 0, v136
	v_max_f32_e32 v137, 0, v137
	v_max_f32_e32 v138, 0, v138
	v_max_f32_e32 v139, 0, v139
	v_pk_mul_f32 v[132:133], v[132:133], v[132:133]
	v_pk_mul_f32 v[134:135], v[134:135], v[134:135]
	v_pk_mul_f32 v[136:137], v[136:137], v[136:137]
	v_pk_mul_f32 v[138:139], v[138:139], v[138:139]
	v_cvt_pk_bf16_f32 v140, v132, v133
	v_cvt_pk_bf16_f32 v141, v134, v135
	v_cvt_pk_bf16_f32 v142, v136, v137
	v_cvt_pk_bf16_f32 v143, v138, v139
	global_store_dwordx4 v129, v[140:143], s[42:43]
	v_pk_mul_f32 v[144:145], v[116:117], v[214:215] op_sel_hi:[1,0]
	v_pk_mul_f32 v[146:147], v[118:119], v[214:215] op_sel_hi:[1,0]
	v_pk_mul_f32 v[148:149], v[112:113], v[214:215] op_sel_hi:[1,0]
	v_pk_mul_f32 v[150:151], v[114:115], v[214:215] op_sel_hi:[1,0]
	v_max_f32_e32 v144, 0, v144
	v_max_f32_e32 v145, 0, v145
	v_max_f32_e32 v146, 0, v146
	v_max_f32_e32 v147, 0, v147
	v_max_f32_e32 v148, 0, v148
	v_max_f32_e32 v149, 0, v149
	v_max_f32_e32 v150, 0, v150
	v_max_f32_e32 v151, 0, v151
	v_pk_mul_f32 v[144:145], v[144:145], v[144:145]
	v_pk_mul_f32 v[146:147], v[146:147], v[146:147]
	v_pk_mul_f32 v[148:149], v[148:149], v[148:149]
	v_pk_mul_f32 v[150:151], v[150:151], v[150:151]
	v_cvt_pk_bf16_f32 v152, v144, v145
	v_cvt_pk_bf16_f32 v153, v146, v147
	v_cvt_pk_bf16_f32 v154, v148, v149
	v_cvt_pk_bf16_f32 v155, v150, v151
	global_store_dwordx4 v129, v[152:155], s[42:43] offset:256
	s_add_u32 s42, s42, s46
	s_addc_u32 s43, s43, 0
	s_waitcnt lgkmcnt(6)
	v_pk_mul_f32 v[132:133], v[108:109], v[216:217] op_sel_hi:[1,0]
	v_pk_mul_f32 v[134:135], v[110:111], v[216:217] op_sel_hi:[1,0]
	v_pk_mul_f32 v[136:137], v[104:105], v[216:217] op_sel_hi:[1,0]
	v_pk_mul_f32 v[138:139], v[106:107], v[216:217] op_sel_hi:[1,0]
	v_max_f32_e32 v132, 0, v132
	v_max_f32_e32 v133, 0, v133
	v_max_f32_e32 v134, 0, v134
	v_max_f32_e32 v135, 0, v135
	v_max_f32_e32 v136, 0, v136
	v_max_f32_e32 v137, 0, v137
	v_max_f32_e32 v138, 0, v138
	v_max_f32_e32 v139, 0, v139
	v_pk_mul_f32 v[132:133], v[132:133], v[132:133]
	v_pk_mul_f32 v[134:135], v[134:135], v[134:135]
	v_pk_mul_f32 v[136:137], v[136:137], v[136:137]
	v_pk_mul_f32 v[138:139], v[138:139], v[138:139]
	v_cvt_pk_bf16_f32 v140, v132, v133
	v_cvt_pk_bf16_f32 v141, v134, v135
	v_cvt_pk_bf16_f32 v142, v136, v137
	v_cvt_pk_bf16_f32 v143, v138, v139
	global_store_dwordx4 v129, v[140:143], s[42:43]
	v_pk_mul_f32 v[144:145], v[100:101], v[216:217] op_sel_hi:[1,0]
	v_pk_mul_f32 v[146:147], v[102:103], v[216:217] op_sel_hi:[1,0]
	v_pk_mul_f32 v[148:149], v[96:97], v[216:217] op_sel_hi:[1,0]
	v_pk_mul_f32 v[150:151], v[98:99], v[216:217] op_sel_hi:[1,0]
	v_max_f32_e32 v144, 0, v144
	v_max_f32_e32 v145, 0, v145
	v_max_f32_e32 v146, 0, v146
	v_max_f32_e32 v147, 0, v147
	v_max_f32_e32 v148, 0, v148
	v_max_f32_e32 v149, 0, v149
	v_max_f32_e32 v150, 0, v150
	v_max_f32_e32 v151, 0, v151
	v_pk_mul_f32 v[144:145], v[144:145], v[144:145]
	v_pk_mul_f32 v[146:147], v[146:147], v[146:147]
	v_pk_mul_f32 v[148:149], v[148:149], v[148:149]
	v_pk_mul_f32 v[150:151], v[150:151], v[150:151]
	v_cvt_pk_bf16_f32 v152, v144, v145
	v_cvt_pk_bf16_f32 v153, v146, v147
	v_cvt_pk_bf16_f32 v154, v148, v149
	v_cvt_pk_bf16_f32 v155, v150, v151
	global_store_dwordx4 v129, v[152:155], s[42:43] offset:256
	s_add_u32 s42, s42, s46
	s_addc_u32 s43, s43, 0
	s_waitcnt lgkmcnt(5)
	v_pk_mul_f32 v[132:133], v[92:93], v[218:219] op_sel_hi:[1,0]
	v_pk_mul_f32 v[134:135], v[94:95], v[218:219] op_sel_hi:[1,0]
	v_pk_mul_f32 v[136:137], v[88:89], v[218:219] op_sel_hi:[1,0]
	v_pk_mul_f32 v[138:139], v[90:91], v[218:219] op_sel_hi:[1,0]
	v_max_f32_e32 v132, 0, v132
	v_max_f32_e32 v133, 0, v133
	v_max_f32_e32 v134, 0, v134
	v_max_f32_e32 v135, 0, v135
	v_max_f32_e32 v136, 0, v136
	v_max_f32_e32 v137, 0, v137
	v_max_f32_e32 v138, 0, v138
	v_max_f32_e32 v139, 0, v139
	v_pk_mul_f32 v[132:133], v[132:133], v[132:133]
	v_pk_mul_f32 v[134:135], v[134:135], v[134:135]
	v_pk_mul_f32 v[136:137], v[136:137], v[136:137]
	v_pk_mul_f32 v[138:139], v[138:139], v[138:139]
	v_cvt_pk_bf16_f32 v140, v132, v133
	v_cvt_pk_bf16_f32 v141, v134, v135
	v_cvt_pk_bf16_f32 v142, v136, v137
	v_cvt_pk_bf16_f32 v143, v138, v139
	global_store_dwordx4 v129, v[140:143], s[42:43]
	v_pk_mul_f32 v[144:145], v[84:85], v[218:219] op_sel_hi:[1,0]
	v_pk_mul_f32 v[146:147], v[86:87], v[218:219] op_sel_hi:[1,0]
	v_pk_mul_f32 v[148:149], v[80:81], v[218:219] op_sel_hi:[1,0]
	v_pk_mul_f32 v[150:151], v[82:83], v[218:219] op_sel_hi:[1,0]
	v_max_f32_e32 v144, 0, v144
	v_max_f32_e32 v145, 0, v145
	v_max_f32_e32 v146, 0, v146
	v_max_f32_e32 v147, 0, v147
	v_max_f32_e32 v148, 0, v148
	v_max_f32_e32 v149, 0, v149
	v_max_f32_e32 v150, 0, v150
	v_max_f32_e32 v151, 0, v151
	v_pk_mul_f32 v[144:145], v[144:145], v[144:145]
	v_pk_mul_f32 v[146:147], v[146:147], v[146:147]
	v_pk_mul_f32 v[148:149], v[148:149], v[148:149]
	v_pk_mul_f32 v[150:151], v[150:151], v[150:151]
	v_cvt_pk_bf16_f32 v152, v144, v145
	v_cvt_pk_bf16_f32 v153, v146, v147
	v_cvt_pk_bf16_f32 v154, v148, v149
	v_cvt_pk_bf16_f32 v155, v150, v151
	global_store_dwordx4 v129, v[152:155], s[42:43] offset:256
	s_add_u32 s42, s42, s46
	s_addc_u32 s43, s43, 0
	s_waitcnt lgkmcnt(4)
	v_pk_mul_f32 v[132:133], v[76:77], v[220:221] op_sel_hi:[1,0]
	v_pk_mul_f32 v[134:135], v[78:79], v[220:221] op_sel_hi:[1,0]
	v_pk_mul_f32 v[136:137], v[72:73], v[220:221] op_sel_hi:[1,0]
	v_pk_mul_f32 v[138:139], v[74:75], v[220:221] op_sel_hi:[1,0]
	v_max_f32_e32 v132, 0, v132
	v_max_f32_e32 v133, 0, v133
	v_max_f32_e32 v134, 0, v134
	v_max_f32_e32 v135, 0, v135
	v_max_f32_e32 v136, 0, v136
	v_max_f32_e32 v137, 0, v137
	v_max_f32_e32 v138, 0, v138
	v_max_f32_e32 v139, 0, v139
	v_pk_mul_f32 v[132:133], v[132:133], v[132:133]
	v_pk_mul_f32 v[134:135], v[134:135], v[134:135]
	v_pk_mul_f32 v[136:137], v[136:137], v[136:137]
	v_pk_mul_f32 v[138:139], v[138:139], v[138:139]
	v_cvt_pk_bf16_f32 v140, v132, v133
	v_cvt_pk_bf16_f32 v141, v134, v135
	v_cvt_pk_bf16_f32 v142, v136, v137
	v_cvt_pk_bf16_f32 v143, v138, v139
	global_store_dwordx4 v129, v[140:143], s[42:43]
	v_pk_mul_f32 v[144:145], v[68:69], v[220:221] op_sel_hi:[1,0]
	v_pk_mul_f32 v[146:147], v[70:71], v[220:221] op_sel_hi:[1,0]
	v_pk_mul_f32 v[148:149], v[64:65], v[220:221] op_sel_hi:[1,0]
	v_pk_mul_f32 v[150:151], v[66:67], v[220:221] op_sel_hi:[1,0]
	v_max_f32_e32 v144, 0, v144
	v_max_f32_e32 v145, 0, v145
	v_max_f32_e32 v146, 0, v146
	v_max_f32_e32 v147, 0, v147
	v_max_f32_e32 v148, 0, v148
	v_max_f32_e32 v149, 0, v149
	v_max_f32_e32 v150, 0, v150
	v_max_f32_e32 v151, 0, v151
	v_pk_mul_f32 v[144:145], v[144:145], v[144:145]
	v_pk_mul_f32 v[146:147], v[146:147], v[146:147]
	v_pk_mul_f32 v[148:149], v[148:149], v[148:149]
	v_pk_mul_f32 v[150:151], v[150:151], v[150:151]
	v_cvt_pk_bf16_f32 v152, v144, v145
	v_cvt_pk_bf16_f32 v153, v146, v147
	v_cvt_pk_bf16_f32 v154, v148, v149
	v_cvt_pk_bf16_f32 v155, v150, v151
	global_store_dwordx4 v129, v[152:155], s[42:43] offset:256
	s_add_u32 s42, s42, s46
	s_addc_u32 s43, s43, 0
	s_add_u32 s42, s42, s47
	s_addc_u32 s43, s43, 0
	s_waitcnt lgkmcnt(3)
	v_pk_mul_f32 v[132:133], v[60:61], v[222:223] op_sel_hi:[1,0]
	v_pk_mul_f32 v[134:135], v[62:63], v[222:223] op_sel_hi:[1,0]
	v_pk_mul_f32 v[136:137], v[56:57], v[222:223] op_sel_hi:[1,0]
	v_pk_mul_f32 v[138:139], v[58:59], v[222:223] op_sel_hi:[1,0]
	v_max_f32_e32 v132, 0, v132
	v_max_f32_e32 v133, 0, v133
	v_max_f32_e32 v134, 0, v134
	v_max_f32_e32 v135, 0, v135
	v_max_f32_e32 v136, 0, v136
	v_max_f32_e32 v137, 0, v137
	v_max_f32_e32 v138, 0, v138
	v_max_f32_e32 v139, 0, v139
	v_pk_mul_f32 v[132:133], v[132:133], v[132:133]
	v_pk_mul_f32 v[134:135], v[134:135], v[134:135]
	v_pk_mul_f32 v[136:137], v[136:137], v[136:137]
	v_pk_mul_f32 v[138:139], v[138:139], v[138:139]
	v_cvt_pk_bf16_f32 v140, v132, v133
	v_cvt_pk_bf16_f32 v141, v134, v135
	v_cvt_pk_bf16_f32 v142, v136, v137
	v_cvt_pk_bf16_f32 v143, v138, v139
	global_store_dwordx4 v129, v[140:143], s[42:43]
	v_pk_mul_f32 v[144:145], v[52:53], v[222:223] op_sel_hi:[1,0]
	v_pk_mul_f32 v[146:147], v[54:55], v[222:223] op_sel_hi:[1,0]
	v_pk_mul_f32 v[148:149], v[48:49], v[222:223] op_sel_hi:[1,0]
	v_pk_mul_f32 v[150:151], v[50:51], v[222:223] op_sel_hi:[1,0]
	v_max_f32_e32 v144, 0, v144
	v_max_f32_e32 v145, 0, v145
	v_max_f32_e32 v146, 0, v146
	v_max_f32_e32 v147, 0, v147
	v_max_f32_e32 v148, 0, v148
	v_max_f32_e32 v149, 0, v149
	v_max_f32_e32 v150, 0, v150
	v_max_f32_e32 v151, 0, v151
	v_pk_mul_f32 v[144:145], v[144:145], v[144:145]
	v_pk_mul_f32 v[146:147], v[146:147], v[146:147]
	v_pk_mul_f32 v[148:149], v[148:149], v[148:149]
	v_pk_mul_f32 v[150:151], v[150:151], v[150:151]
	v_cvt_pk_bf16_f32 v152, v144, v145
	v_cvt_pk_bf16_f32 v153, v146, v147
	v_cvt_pk_bf16_f32 v154, v148, v149
	v_cvt_pk_bf16_f32 v155, v150, v151
	global_store_dwordx4 v129, v[152:155], s[42:43] offset:256
	s_add_u32 s42, s42, s46
	s_addc_u32 s43, s43, 0
	s_waitcnt lgkmcnt(2)
	v_pk_mul_f32 v[132:133], v[44:45], v[224:225] op_sel_hi:[1,0]
	v_pk_mul_f32 v[134:135], v[46:47], v[224:225] op_sel_hi:[1,0]
	v_pk_mul_f32 v[136:137], v[40:41], v[224:225] op_sel_hi:[1,0]
	v_pk_mul_f32 v[138:139], v[42:43], v[224:225] op_sel_hi:[1,0]
	v_max_f32_e32 v132, 0, v132
	v_max_f32_e32 v133, 0, v133
	v_max_f32_e32 v134, 0, v134
	v_max_f32_e32 v135, 0, v135
	v_max_f32_e32 v136, 0, v136
	v_max_f32_e32 v137, 0, v137
	v_max_f32_e32 v138, 0, v138
	v_max_f32_e32 v139, 0, v139
	v_pk_mul_f32 v[132:133], v[132:133], v[132:133]
	v_pk_mul_f32 v[134:135], v[134:135], v[134:135]
	v_pk_mul_f32 v[136:137], v[136:137], v[136:137]
	v_pk_mul_f32 v[138:139], v[138:139], v[138:139]
	v_cvt_pk_bf16_f32 v140, v132, v133
	v_cvt_pk_bf16_f32 v141, v134, v135
	v_cvt_pk_bf16_f32 v142, v136, v137
	v_cvt_pk_bf16_f32 v143, v138, v139
	global_store_dwordx4 v129, v[140:143], s[42:43]
	v_pk_mul_f32 v[144:145], v[36:37], v[224:225] op_sel_hi:[1,0]
	v_pk_mul_f32 v[146:147], v[38:39], v[224:225] op_sel_hi:[1,0]
	v_pk_mul_f32 v[148:149], v[32:33], v[224:225] op_sel_hi:[1,0]
	v_pk_mul_f32 v[150:151], v[34:35], v[224:225] op_sel_hi:[1,0]
	v_max_f32_e32 v144, 0, v144
	v_max_f32_e32 v145, 0, v145
	v_max_f32_e32 v146, 0, v146
	v_max_f32_e32 v147, 0, v147
	v_max_f32_e32 v148, 0, v148
	v_max_f32_e32 v149, 0, v149
	v_max_f32_e32 v150, 0, v150
	v_max_f32_e32 v151, 0, v151
	v_pk_mul_f32 v[144:145], v[144:145], v[144:145]
	v_pk_mul_f32 v[146:147], v[146:147], v[146:147]
	v_pk_mul_f32 v[148:149], v[148:149], v[148:149]
	v_pk_mul_f32 v[150:151], v[150:151], v[150:151]
	v_cvt_pk_bf16_f32 v152, v144, v145
	v_cvt_pk_bf16_f32 v153, v146, v147
	v_cvt_pk_bf16_f32 v154, v148, v149
	v_cvt_pk_bf16_f32 v155, v150, v151
	global_store_dwordx4 v129, v[152:155], s[42:43] offset:256
	s_add_u32 s42, s42, s46
	s_addc_u32 s43, s43, 0
	s_waitcnt lgkmcnt(1)
	v_pk_mul_f32 v[132:133], v[28:29], v[226:227] op_sel_hi:[1,0]
	v_pk_mul_f32 v[134:135], v[30:31], v[226:227] op_sel_hi:[1,0]
	v_pk_mul_f32 v[136:137], v[24:25], v[226:227] op_sel_hi:[1,0]
	v_pk_mul_f32 v[138:139], v[26:27], v[226:227] op_sel_hi:[1,0]
	v_max_f32_e32 v132, 0, v132
	v_max_f32_e32 v133, 0, v133
	v_max_f32_e32 v134, 0, v134
	v_max_f32_e32 v135, 0, v135
	v_max_f32_e32 v136, 0, v136
	v_max_f32_e32 v137, 0, v137
	v_max_f32_e32 v138, 0, v138
	v_max_f32_e32 v139, 0, v139
	v_pk_mul_f32 v[132:133], v[132:133], v[132:133]
	v_pk_mul_f32 v[134:135], v[134:135], v[134:135]
	v_pk_mul_f32 v[136:137], v[136:137], v[136:137]
	v_pk_mul_f32 v[138:139], v[138:139], v[138:139]
	v_cvt_pk_bf16_f32 v140, v132, v133
	v_cvt_pk_bf16_f32 v141, v134, v135
	v_cvt_pk_bf16_f32 v142, v136, v137
	v_cvt_pk_bf16_f32 v143, v138, v139
	global_store_dwordx4 v129, v[140:143], s[42:43]
	v_pk_mul_f32 v[144:145], v[20:21], v[226:227] op_sel_hi:[1,0]
	v_pk_mul_f32 v[146:147], v[22:23], v[226:227] op_sel_hi:[1,0]
	v_pk_mul_f32 v[148:149], v[16:17], v[226:227] op_sel_hi:[1,0]
	v_pk_mul_f32 v[150:151], v[18:19], v[226:227] op_sel_hi:[1,0]
	v_max_f32_e32 v144, 0, v144
	v_max_f32_e32 v145, 0, v145
	v_max_f32_e32 v146, 0, v146
	v_max_f32_e32 v147, 0, v147
	v_max_f32_e32 v148, 0, v148
	v_max_f32_e32 v149, 0, v149
	v_max_f32_e32 v150, 0, v150
	v_max_f32_e32 v151, 0, v151
	v_pk_mul_f32 v[144:145], v[144:145], v[144:145]
	v_pk_mul_f32 v[146:147], v[146:147], v[146:147]
	v_pk_mul_f32 v[148:149], v[148:149], v[148:149]
	v_pk_mul_f32 v[150:151], v[150:151], v[150:151]
	v_cvt_pk_bf16_f32 v152, v144, v145
	v_cvt_pk_bf16_f32 v153, v146, v147
	v_cvt_pk_bf16_f32 v154, v148, v149
	v_cvt_pk_bf16_f32 v155, v150, v151
	global_store_dwordx4 v129, v[152:155], s[42:43] offset:256
	s_add_u32 s42, s42, s46
	s_addc_u32 s43, s43, 0
	s_waitcnt lgkmcnt(0)
	v_pk_mul_f32 v[132:133], v[12:13], v[228:229] op_sel_hi:[1,0]
	v_pk_mul_f32 v[134:135], v[14:15], v[228:229] op_sel_hi:[1,0]
	v_pk_mul_f32 v[136:137], v[8:9], v[228:229] op_sel_hi:[1,0]
	v_pk_mul_f32 v[138:139], v[10:11], v[228:229] op_sel_hi:[1,0]
	v_max_f32_e32 v132, 0, v132
	v_max_f32_e32 v133, 0, v133
	v_max_f32_e32 v134, 0, v134
	v_max_f32_e32 v135, 0, v135
	v_max_f32_e32 v136, 0, v136
	v_max_f32_e32 v137, 0, v137
	v_max_f32_e32 v138, 0, v138
	v_max_f32_e32 v139, 0, v139
	v_pk_mul_f32 v[132:133], v[132:133], v[132:133]
	v_pk_mul_f32 v[134:135], v[134:135], v[134:135]
	v_pk_mul_f32 v[136:137], v[136:137], v[136:137]
	v_pk_mul_f32 v[138:139], v[138:139], v[138:139]
	v_cvt_pk_bf16_f32 v140, v132, v133
	v_cvt_pk_bf16_f32 v141, v134, v135
	v_cvt_pk_bf16_f32 v142, v136, v137
	v_cvt_pk_bf16_f32 v143, v138, v139
	global_store_dwordx4 v129, v[140:143], s[42:43]
	v_pk_mul_f32 v[144:145], v[4:5], v[228:229] op_sel_hi:[1,0]
	v_pk_mul_f32 v[146:147], v[6:7], v[228:229] op_sel_hi:[1,0]
	v_pk_mul_f32 v[148:149], v[0:1], v[228:229] op_sel_hi:[1,0]
	v_pk_mul_f32 v[150:151], v[2:3], v[228:229] op_sel_hi:[1,0]
	v_max_f32_e32 v144, 0, v144
	v_max_f32_e32 v145, 0, v145
	v_max_f32_e32 v146, 0, v146
	v_max_f32_e32 v147, 0, v147
	v_max_f32_e32 v148, 0, v148
	v_max_f32_e32 v149, 0, v149
	v_max_f32_e32 v150, 0, v150
	v_max_f32_e32 v151, 0, v151
	v_pk_mul_f32 v[144:145], v[144:145], v[144:145]
	v_pk_mul_f32 v[146:147], v[146:147], v[146:147]
	v_pk_mul_f32 v[148:149], v[148:149], v[148:149]
	v_pk_mul_f32 v[150:151], v[150:151], v[150:151]
	v_cvt_pk_bf16_f32 v152, v144, v145
	v_cvt_pk_bf16_f32 v153, v146, v147
	v_cvt_pk_bf16_f32 v154, v148, v149
	v_cvt_pk_bf16_f32 v155, v150, v151
	global_store_dwordx4 v129, v[152:155], s[42:43] offset:256
	s_mov_b64 s[40:41], 0

.LBB0_374:
	v_readlane_b32 s8, v246, 37
	v_readlane_b32 s14, v246, 43
	v_readlane_b32 s9, v246, 38
	v_readlane_b32 s10, v246, 39
	v_readlane_b32 s11, v246, 40
	v_readlane_b32 s12, v246, 41
	v_readlane_b32 s13, v246, 42
	v_readlane_b32 s15, v246, 44
	s_add_i32 s14, s14, 1
	v_writelane_b32 v246, s8, 37
	s_cmp_ge_i32 s14, s15
	s_mov_b64 s[0:1], -1
	v_writelane_b32 v246, s9, 38
	v_writelane_b32 v246, s10, 39
	v_writelane_b32 v246, s11, 40
	v_writelane_b32 v246, s12, 41
	v_writelane_b32 v246, s13, 42
	v_writelane_b32 v246, s14, 43
	s_movk_i32 s5, 0x7fff
	v_writelane_b32 v246, s15, 44
	s_cbranch_scc1 .LBB0_21
	s_waitcnt vmcnt(0)
	s_waitcnt vmcnt(0) lgkmcnt(0)
	s_barrier
	s_mov_b64 s[0:1], exec
	v_readlane_b32 s2, v247, 3
	v_readlane_b32 s3, v247, 4
	s_and_b64 s[2:3], s[0:1], s[2:3]
	s_mov_b64 exec, s[2:3]
	s_cbranch_execz .LBB0_20
	v_readlane_b32 s2, v248, 2
	s_waitcnt vmcnt(0) expcnt(0) lgkmcnt(0)
	s_nop 1
	v_mov_b32_e32 v2, s2
	v_readlane_b32 s3, v248, 3
	s_nop 1
	v_cmp_ne_u32_e32 vcc, 0, v2
	v_mov_b32_e32 v0, s3
	s_cbranch_vccnz .LBB0_391
	s_mov_b32 s5, 1
	s_branch .LBB0_379

.LBB0_390:
	v_readlane_b32 s2, v246, 29
	v_readlane_b32 s3, v246, 30
	v_cmp_ne_u32_e32 vcc, 0, v0
	s_nop 0
	v_cndmask_b32_e64 v16, 0, v0, s[2:3]
	v_readlane_b32 s2, v246, 27
	v_readlane_b32 s3, v246, 28
	v_cndmask_b32_e64 v0, 0, 1, vcc
	v_cmp_ne_u32_e32 vcc, 0, v1
	v_cndmask_b32_e64 v16, v16, v1, s[2:3]
	v_readlane_b32 s2, v246, 25
	v_readlane_b32 s3, v246, 26
	v_addc_co_u32_e32 v0, vcc, 0, v0, vcc
	s_nop 0
	v_cndmask_b32_e64 v16, v16, v2, s[2:3]
	v_readlane_b32 s2, v246, 23
	v_readlane_b32 s3, v246, 24
	v_cmp_ne_u32_e32 vcc, 0, v2
	s_nop 0
	v_cndmask_b32_e64 v16, v16, v3, s[2:3]
	v_readlane_b32 s2, v246, 21
	v_readlane_b32 s3, v246, 22
	v_cndmask_b32_e64 v1, 0, 1, vcc
	v_cmp_ne_u32_e32 vcc, 0, v3
	v_cndmask_b32_e64 v16, v16, v4, s[2:3]
	v_readlane_b32 s2, v246, 19
	v_readlane_b32 s3, v246, 20
	v_addc_co_u32_e32 v0, vcc, v0, v1, vcc
	s_nop 0
	v_cndmask_b32_e64 v16, v16, v5, s[2:3]
	v_readlane_b32 s2, v246, 17
	v_readlane_b32 s3, v246, 18
	v_cmp_ne_u32_e32 vcc, 0, v4
	s_nop 0
	v_cndmask_b32_e64 v16, v16, v6, s[2:3]
	v_readlane_b32 s2, v246, 15
	v_readlane_b32 s3, v246, 16
	v_cndmask_b32_e64 v1, 0, 1, vcc
	v_cmp_ne_u32_e32 vcc, 0, v5
	v_cndmask_b32_e64 v16, v16, v7, s[2:3]
	v_readlane_b32 s2, v246, 13
	v_readlane_b32 s3, v246, 14
	v_addc_co_u32_e32 v0, vcc, v0, v1, vcc
	s_nop 0
	v_cndmask_b32_e64 v16, v16, v8, s[2:3]
	v_readlane_b32 s2, v246, 11
	v_readlane_b32 s3, v246, 12
	v_cmp_ne_u32_e32 vcc, 0, v6
	s_nop 0
	v_cndmask_b32_e64 v16, v16, v9, s[2:3]
	v_readlane_b32 s2, v246, 9
	v_cndmask_b32_e64 v1, 0, 1, vcc
	v_cmp_ne_u32_e32 vcc, 0, v7
	v_readlane_b32 s3, v246, 10
	s_nop 0
	v_addc_co_u32_e32 v0, vcc, v0, v1, vcc
	v_cndmask_b32_e64 v16, v16, v10, s[2:3]
	v_readlane_b32 s2, v246, 7
	v_cmp_ne_u32_e32 vcc, 0, v8
	v_readlane_b32 s3, v246, 8
	s_nop 0
	v_cndmask_b32_e64 v1, 0, 1, vcc
	v_cmp_ne_u32_e32 vcc, 0, v9
	v_cndmask_b32_e64 v16, v16, v11, s[2:3]
	v_readlane_b32 s2, v246, 5
	v_addc_co_u32_e32 v0, vcc, v0, v1, vcc
	v_readlane_b32 s3, v246, 6
	v_cmp_ne_u32_e32 vcc, 0, v10
	s_nop 0
	v_cndmask_b32_e64 v16, v16, v12, s[2:3]
	v_readlane_b32 s2, v246, 3
	v_cndmask_b32_e64 v1, 0, 1, vcc
	v_cmp_ne_u32_e32 vcc, 0, v11
	v_readlane_b32 s3, v246, 4
	s_nop 0
	v_addc_co_u32_e32 v0, vcc, v0, v1, vcc
	v_cndmask_b32_e64 v16, v16, v13, s[2:3]
	v_readlane_b32 s2, v246, 1
	v_cmp_ne_u32_e32 vcc, 0, v12
	v_readlane_b32 s3, v246, 2
	s_nop 0
	v_cndmask_b32_e64 v1, 0, 1, vcc
	v_cmp_ne_u32_e32 vcc, 0, v13
	v_cndmask_b32_e64 v16, v16, v14, s[2:3]
	v_readlane_b32 s2, v247, 63
	v_addc_co_u32_e32 v0, vcc, v0, v1, vcc
	v_readlane_b32 s3, v246, 0
	v_cmp_ne_u32_e32 vcc, 0, v14
	s_nop 0
	v_cndmask_b32_e64 v16, v16, v15, s[2:3]
	v_cndmask_b32_e64 v1, 0, 1, vcc
	v_cmp_ne_u32_e32 vcc, 0, v15
	v_max_u32_e32 v2, 1, v16
	s_nop 1
	v_addc_co_u32_e32 v0, vcc, v0, v1, vcc
	s_nop 1
	v_max_u32_e32 v0, 1, v0
	v_readfirstlane_b32 s2, v2
	s_nop 0
	v_readfirstlane_b32 s3, v0
	s_nop 3
	v_writelane_b32 v248, s2, 2
	v_writelane_b32 v248, s3, 3

	.amdhsa_kernel _Z8mega_fwd4Args
		.amdhsa_group_segment_fixed_size 16384
		.amdhsa_private_segment_fixed_size 0
		.amdhsa_kernarg_size 416
		.amdhsa_user_sgpr_count 2
		.amdhsa_user_sgpr_dispatch_ptr 0
		.amdhsa_user_sgpr_queue_ptr 0
		.amdhsa_user_sgpr_kernarg_segment_ptr 1
		.amdhsa_user_sgpr_dispatch_id 0
		.amdhsa_user_sgpr_kernarg_preload_length 0
		.amdhsa_user_sgpr_kernarg_preload_offset 0
		.amdhsa_user_sgpr_private_segment_size 0
		.amdhsa_uses_dynamic_stack 0
		.amdhsa_enable_private_segment 0
		.amdhsa_system_sgpr_workgroup_id_x 1
		.amdhsa_system_sgpr_workgroup_id_y 0
		.amdhsa_system_sgpr_workgroup_id_z 0
		.amdhsa_system_sgpr_workgroup_info 0
		.amdhsa_system_vgpr_workitem_id 2
		.amdhsa_next_free_vgpr 252
		.amdhsa_next_free_sgpr 100
		.amdhsa_accum_offset 252
		.amdhsa_reserve_vcc 1
		.amdhsa_float_round_mode_32 0
		.amdhsa_float_round_mode_16_64 0
		.amdhsa_float_denorm_mode_32 3
		.amdhsa_float_denorm_mode_16_64 3
		.amdhsa_dx10_clamp 1
		.amdhsa_ieee_mode 1
		.amdhsa_fp16_overflow 0
		.amdhsa_tg_split 0
		.amdhsa_exception_fp_ieee_invalid_op 0
		.amdhsa_exception_fp_denorm_src 0
		.amdhsa_exception_fp_ieee_div_zero 0
		.amdhsa_exception_fp_ieee_overflow 0
		.amdhsa_exception_fp_ieee_underflow 0
		.amdhsa_exception_fp_ieee_inexact 0
		.amdhsa_exception_int_div_zero 0
	.end_amdhsa_kernel

amdhsa.kernels:
  - .agpr_count:     0
    .args:
      - .offset:         0
        .size:           160
        .value_kind:     by_value
      - .offset:         160
        .size:           4
        .value_kind:     hidden_block_count_x
      - .offset:         164
        .size:           4
        .value_kind:     hidden_block_count_y
      - .offset:         168
        .size:           4
        .value_kind:     hidden_block_count_z
      - .offset:         172
        .size:           2
        .value_kind:     hidden_group_size_x
      - .offset:         174
        .size:           2
        .value_kind:     hidden_group_size_y
      - .offset:         176
        .size:           2
        .value_kind:     hidden_group_size_z
      - .offset:         178
        .size:           2
        .value_kind:     hidden_remainder_x
      - .offset:         180
        .size:           2
        .value_kind:     hidden_remainder_y
      - .offset:         182
        .size:           2
        .value_kind:     hidden_remainder_z
      - .offset:         200
        .size:           8
        .value_kind:     hidden_global_offset_x
      - .offset:         208
        .size:           8
        .value_kind:     hidden_global_offset_y
      - .offset:         216
        .size:           8
        .value_kind:     hidden_global_offset_z
      - .offset:         224
        .size:           2
        .value_kind:     hidden_grid_dims
      - .offset:         248
        .size:           8
        .value_kind:     hidden_multigrid_sync_arg
      - .offset:         280
        .size:           4
        .value_kind:     hidden_dynamic_lds_size
    .group_segment_fixed_size: 16384
    .kernarg_segment_align: 8
    .kernarg_segment_size: 416
    .language:       OpenCL C
    .language_version:
      - 2
      - 0
    .max_flat_workgroup_size: 512
    .name:           _Z8mega_fwd4Args
    .private_segment_fixed_size: 0
    .sgpr_count:     106
    .sgpr_spill_count: 209
    .symbol:         _Z8mega_fwd4Args.kd
    .uniform_work_group_size: 1
    .uses_dynamic_stack: false
    .vgpr_count:     252
    .vgpr_spill_count: 0
    .wavefront_size: 64
